# MLA epilogue: eight 8-byte stores per lane paired into four 16-byte stores via permlane32_swap (as the dilated epilogue)
# baseline (speedup 1.0000x reference)
.LBB0_541:
	s_or_b32 s10, s78, 3
	s_mul_hi_u32 s54, s10, 0x2aaaaaab
	s_mul_i32 s54, s54, 6
	s_sub_i32 s10, s10, s54
	s_mulk_i32 s10, 0x5000
	v_add_u32_e32 v0, s10, v106
	ds_read_b64_tr_b16 v[58:59], v0 offset:12288
	ds_read_b64_tr_b16 v[60:61], v0 offset:12800
	ds_read_b64_tr_b16 v[62:63], v0 offset:13312
	ds_read_b64_tr_b16 v[64:65], v0 offset:13824
	ds_read_b64_tr_b16 v[66:67], v0 offset:14336
	ds_read_b64_tr_b16 v[68:69], v0 offset:14848
	ds_read_b64_tr_b16 v[70:71], v0 offset:15360
	ds_read_b64_tr_b16 v[72:73], v0 offset:15872
	ds_read_b64_tr_b16 v[74:75], v0 offset:16384
	ds_read_b64_tr_b16 v[76:77], v0 offset:16896
	ds_read_b64_tr_b16 v[78:79], v0 offset:17408
	ds_read_b64_tr_b16 v[80:81], v0 offset:17920
	ds_read_b64_tr_b16 v[98:99], v0 offset:18432
	ds_read_b64_tr_b16 v[100:101], v0 offset:18944
	ds_read_b64_tr_b16 v[102:103], v0 offset:19456
	ds_read_b64_tr_b16 v[104:105], v0 offset:19968
	v_mov_b32_e32 v0, v186
	s_waitcnt lgkmcnt(0)
	s_barrier
	v_mov_b32_e32 v53, s53
	v_ashrrev_i32_e32 v50, 1, v0
	v_and_b32_e32 v50, 0xffffffe0, v50
	v_and_or_b32 v52, v0, 31, s19
	v_ashrrev_i32_e32 v51, 31, v50
	v_or_b32_e32 v52, s52, v52
	v_lshl_add_u64 v[50:51], v[52:53], 0, v[50:51]
	v_mov_b64_e32 v[52:53], s[16:17]
	v_mad_u64_u32 v[52:53], s[52:53], v50, s66, v[52:53]
	v_mad_i32_i24 v53, v51, s66, v53
	s_mov_b32 s19, s11
	v_lshrrev_b32_e32 v0, 2, v0
	v_lshl_add_u64 v[52:53], v[52:53], 0, s[18:19]
	v_and_b32_e32 v0, 8, v0
	v_lshl_add_u64 v[112:113], v[52:53], 0, v[0:1]
	s_movk_i32 s10, 0x1000
	v_add_co_u32_e32 v52, vcc, s10, v112
	v_cvt_pk_bf16_f32 v108, v82, v83
	s_nop 0
	v_addc_co_u32_e32 v53, vcc, 0, v113, vcc
	global_load_dwordx2 v[140:141], v[52:53], off offset:912
	global_load_dwordx2 v[142:143], v[52:53], off offset:928
	global_load_dwordx2 v[144:145], v[52:53], off offset:944
	global_load_dwordx2 v[146:147], v[52:53], off offset:848
	global_load_dwordx2 v[148:149], v[52:53], off offset:864
	global_load_dwordx2 v[150:151], v[52:53], off offset:880
	global_load_dwordx2 v[152:153], v[52:53], off offset:896
	global_load_dwordx2 v[52:53], v[52:53], off offset:832
	v_cvt_pk_bf16_f32 v109, v84, v85
	v_cvt_pk_bf16_f32 v110, v86, v87
	v_cvt_pk_bf16_f32 v111, v88, v89
	v_add_f32_e32 v57, v82, v34
	v_add_f32_e32 v82, v83, v35
	s_waitcnt lgkmcnt(14)
	v_mfma_f32_32x32x16_bf16 v[18:33], v[58:61], v[108:111], v[18:33]
	v_add_f32_e32 v83, v84, v36
	v_add_f32_e32 v84, v85, v37
	v_add_f32_e32 v85, v86, v38
	v_cvt_pk_bf16_f32 v34, v34, v35
	v_cvt_pk_bf16_f32 v35, v36, v37
	v_cvt_pk_bf16_f32 v36, v38, v39
	v_add_f32_e32 v38, 0, v57
	s_waitcnt lgkmcnt(6)
	v_mfma_f32_32x32x16_bf16 v[2:17], v[74:77], v[108:111], v[2:17]
	v_cvt_pk_bf16_f32 v58, v90, v91
	v_cvt_pk_bf16_f32 v59, v92, v93
	v_cvt_pk_bf16_f32 v60, v94, v95
	v_cvt_pk_bf16_f32 v61, v96, v97
	v_add_f32_e32 v38, v82, v38
	v_add_f32_e32 v38, v83, v38
	v_add_f32_e32 v38, v84, v38
	v_mfma_f32_32x32x16_bf16 v[18:33], v[62:65], v[58:61], v[18:33]
	v_add_f32_e32 v86, v87, v39
	v_add_f32_e32 v38, v85, v38
	v_add_f32_e32 v87, v88, v40
	v_add_f32_e32 v38, v86, v38
	v_add_f32_e32 v88, v89, v41
	v_add_f32_e32 v38, v87, v38
	v_add_f32_e32 v74, v90, v42
	s_waitcnt lgkmcnt(4)
	v_mfma_f32_32x32x16_bf16 v[2:17], v[78:81], v[58:61], v[2:17]
	v_add_f32_e32 v38, v88, v38
	v_add_f32_e32 v75, v91, v43
	v_add_f32_e32 v38, v74, v38
	v_add_f32_e32 v76, v92, v44
	v_cvt_pk_bf16_f32 v37, v40, v41
	v_add_f32_e32 v38, v75, v38
	v_add_f32_e32 v77, v93, v45
	v_mfma_f32_32x32x16_bf16 v[18:33], v[66:69], v[34:37], v[18:33]
	v_add_f32_e64 v62, v94, v46
	v_add_f32_e64 v63, v95, v47
	v_add_f32_e64 v64, v96, v48
	v_add_f32_e64 v65, v97, v49
	v_cvt_pk_bf16_f32 v41, v44, v45
	v_cvt_pk_bf16_f32 v40, v42, v43
	v_cvt_pk_bf16_f32 v42, v46, v47
	v_cvt_pk_bf16_f32 v43, v48, v49
	s_waitcnt vmcnt(0)
	v_lshlrev_b32_e32 v57, 16, v52
	s_waitcnt lgkmcnt(2)
	v_mfma_f32_32x32x16_bf16 v[2:17], v[98:101], v[34:37], v[2:17]
	v_add_f32_e32 v34, v76, v38
	v_add_f32_e32 v34, v77, v34
	v_add_f32_e32 v34, v62, v34
	v_add_f32_e32 v34, v63, v34
	v_add_f32_e32 v34, v64, v34
	v_add_f32_e32 v34, v65, v34
	v_add_f32_e32 v34, v107, v34
	v_mov_b32_e32 v35, v34
	s_nop 1
	v_permlane32_swap_b32_e32 v34, v35
	v_add_f32_e32 v38, v34, v35
	v_div_scale_f32 v34, s[52:53], v38, v38, 1.0
	v_rcp_f32_e32 v39, v34
	s_mov_b64 s[52:53], 0x1340
	v_and_b32_e32 v52, 0xffff0000, v52
	v_mul_f32_e32 v48, 0xbfb8aa3b, v57
	v_fma_f32 v35, -v34, v39, 1.0
	v_fmac_f32_e32 v39, v35, v39
	v_div_scale_f32 v35, vcc, 1.0, v38, 1.0
	v_mul_f32_e32 v44, v35, v39
	v_fma_f32 v36, -v34, v44, v35
	v_fmac_f32_e32 v44, v36, v39
	v_fma_f32 v45, -v34, v44, v35
	v_lshl_add_u64 v[34:35], v[112:113], 0, s[52:53]
	v_mul_f32_e32 v49, 0xbfb8aa3b, v52
	v_mfma_f32_32x32x16_bf16 v[18:33], v[70:73], v[40:43], v[18:33]
	v_exp_f32_e32 v48, v48
	v_exp_f32_e32 v49, v49
	v_div_fmas_f32 v39, v45, v39, v44
	v_div_fixup_f32 v38, v39, v38, 1.0
	v_pk_add_f32 v[44:45], v[48:49], 1.0 op_sel_hi:[1,0]
	s_nop 0
	v_div_scale_f32 v39, s[52:53], v45, v45, v52
	s_waitcnt lgkmcnt(0)
	v_mfma_f32_32x32x16_bf16 v[2:17], v[102:105], v[40:43], v[2:17]
	s_nop 7
	v_mov_b32_e32 v36, v140
	v_mov_b32_e32 v37, v141
	v_mov_b32_e32 v40, v142
	v_mov_b32_e32 v41, v143
	v_mov_b32_e32 v42, v144
	v_mov_b32_e32 v43, v145
	v_mov_b32_e32 v46, v146
	v_mov_b32_e32 v47, v147
	v_rcp_f32_e32 v58, v39
	v_lshlrev_b64 v[48:49], 11, v[50:51]
	v_pk_mul_f32 v[18:19], v[18:19], v[38:39] op_sel_hi:[1,0]
	v_lshl_add_u64 v[48:49], s[48:49], 0, v[48:49]
	v_fma_f32 v50, -v39, v58, 1.0
	v_fmac_f32_e32 v58, v50, v58
	v_div_scale_f32 v50, vcc, v52, v45, v52
	v_mul_f32_e32 v51, v50, v58
	v_fma_f32 v59, -v39, v51, v50
	v_fmac_f32_e32 v51, v59, v58
	v_div_scale_f32 v59, s[52:53], v44, v44, v57
	v_rcp_f32_e32 v60, v59
	v_fma_f32 v39, -v39, v51, v50
	v_div_fmas_f32 v39, v39, v58, v51
	v_div_fixup_f32 v45, v39, v45, v52
	v_fma_f32 v39, -v59, v60, 1.0
	v_fmac_f32_e32 v60, v39, v60
	v_div_scale_f32 v39, vcc, v57, v44, v57
	v_mul_f32_e32 v52, v39, v60
	v_fma_f32 v50, -v59, v52, v39
	v_lshlrev_b32_e32 v58, 16, v53
	v_and_b32_e32 v53, 0xffff0000, v53
	v_fmac_f32_e32 v52, v50, v60
	v_mul_f32_e32 v50, 0xbfb8aa3b, v58
	v_mul_f32_e32 v51, 0xbfb8aa3b, v53
	v_exp_f32_e32 v50, v50
	v_exp_f32_e32 v51, v51
	v_fma_f32 v39, -v59, v52, v39
	v_div_fmas_f32 v39, v39, v60, v52
	v_div_fixup_f32 v44, v39, v44, v57
	v_pk_add_f32 v[50:51], v[50:51], 1.0 op_sel_hi:[1,0]
	v_pk_mul_f32 v[20:21], v[20:21], v[38:39] op_sel_hi:[1,0]
	v_div_scale_f32 v52, s[52:53], v51, v51, v53
	v_rcp_f32_e32 v59, v52
	v_pk_mul_f32 v[18:19], v[18:19], v[44:45]
	v_fma_f32 v39, -v52, v59, 1.0
	v_fmac_f32_e32 v59, v39, v59
	v_div_scale_f32 v39, vcc, v53, v51, v53
	v_mul_f32_e32 v44, v39, v59
	v_fma_f32 v45, -v52, v44, v39
	v_fmac_f32_e32 v44, v45, v59
	v_fma_f32 v39, -v52, v44, v39
	v_div_scale_f32 v52, s[52:53], v50, v50, v58
	v_rcp_f32_e32 v57, v52
	v_div_fmas_f32 v39, v39, v59, v44
	v_div_fixup_f32 v45, v39, v51, v53
	v_fma_f32 v39, -v52, v57, 1.0
	v_fmac_f32_e32 v57, v39, v57
	v_div_scale_f32 v39, vcc, v58, v50, v58
	v_mul_f32_e32 v44, v39, v57
	v_fma_f32 v51, -v52, v44, v39
	v_fmac_f32_e32 v44, v51, v57
	v_fma_f32 v39, -v52, v44, v39
	v_div_fmas_f32 v39, v39, v57, v44
	v_div_fixup_f32 v44, v39, v50, v58
	v_mov_b32_e32 v50, v148
	v_mov_b32_e32 v51, v149
	v_mov_b32_e32 v52, v150
	v_mov_b32_e32 v53, v151
	s_nop 0
	v_mov_b32_e32 v34, v152
	v_mov_b32_e32 v35, v153
	v_pk_mul_f32 v[20:21], v[20:21], v[44:45]
	v_cvt_pk_bf16_f32 v44, v18, v19
	v_cvt_pk_bf16_f32 v45, v20, v21
	v_lshl_add_u64 v[18:19], v[48:49], 0, v[0:1]
	v_lshl_add_u64 v[158:159], v[18:19], 0, v[0:1]
	v_mov_b32_e32 v140, v44
	v_mov_b32_e32 v141, v45
	v_lshlrev_b32_e32 v39, 16, v46
	v_and_b32_e32 v46, 0xffff0000, v46
	v_mul_f32_e32 v57, 0xbfb8aa3b, v39
	v_exp_f32_e32 v58, v57
	v_mul_f32_e32 v57, 0xbfb8aa3b, v46
	v_exp_f32_e32 v59, v57
	v_pk_mul_f32 v[22:23], v[22:23], v[38:39] op_sel_hi:[1,0]
	v_pk_add_f32 v[20:21], v[58:59], 1.0 op_sel_hi:[1,0]
	s_nop 0
	v_div_scale_f32 v57, s[52:53], v21, v21, v46
	v_rcp_f32_e32 v58, v57
	v_div_scale_f32 v48, s[52:53], v20, v20, v39
	v_rcp_f32_e32 v49, v48
	v_fma_f32 v0, -v57, v58, 1.0
	v_fmac_f32_e32 v58, v0, v58
	v_div_scale_f32 v0, vcc, v46, v21, v46
	v_mul_f32_e32 v44, v0, v58
	v_fma_f32 v45, -v57, v44, v0
	v_fmac_f32_e32 v44, v45, v58
	v_fma_f32 v0, -v57, v44, v0
	v_div_fmas_f32 v0, v0, v58, v44
	v_div_fixup_f32 v21, v0, v21, v46
	v_fma_f32 v0, -v48, v49, 1.0
	v_fmac_f32_e32 v49, v0, v49
	v_div_scale_f32 v0, vcc, v39, v20, v39
	v_mul_f32_e32 v46, v0, v49
	v_fma_f32 v44, -v48, v46, v0
	v_lshlrev_b32_e32 v57, 16, v47
	v_and_b32_e32 v47, 0xffff0000, v47
	v_fmac_f32_e32 v46, v44, v49
	v_mul_f32_e32 v44, 0xbfb8aa3b, v57
	v_mul_f32_e32 v45, 0xbfb8aa3b, v47
	v_exp_f32_e32 v44, v44
	v_exp_f32_e32 v45, v45
	v_fma_f32 v0, -v48, v46, v0
	v_div_fmas_f32 v0, v0, v49, v46
	v_div_fixup_f32 v20, v0, v20, v39
	v_pk_add_f32 v[44:45], v[44:45], 1.0 op_sel_hi:[1,0]
	v_pk_mul_f32 v[20:21], v[22:23], v[20:21]
	v_div_scale_f32 v46, s[52:53], v45, v45, v47
	v_rcp_f32_e32 v48, v46
	v_pk_mul_f32 v[22:23], v[24:25], v[38:39] op_sel_hi:[1,0]
	v_div_scale_f32 v39, s[52:53], v44, v44, v57
	v_fma_f32 v0, -v46, v48, 1.0
	v_fmac_f32_e32 v48, v0, v48
	v_div_scale_f32 v0, vcc, v47, v45, v47
	v_mul_f32_e32 v24, v0, v48
	v_fma_f32 v25, -v46, v24, v0
	v_fmac_f32_e32 v24, v25, v48
	v_fma_f32 v0, -v46, v24, v0
	v_rcp_f32_e32 v46, v39
	v_div_fmas_f32 v0, v0, v48, v24
	v_div_fixup_f32 v25, v0, v45, v47
	v_cvt_pk_bf16_f32 v20, v20, v21
	v_fma_f32 v0, -v39, v46, 1.0
	v_fmac_f32_e32 v46, v0, v46
	v_div_scale_f32 v0, vcc, v57, v44, v57
	v_mul_f32_e32 v24, v0, v46
	v_fma_f32 v45, -v39, v24, v0
	v_fmac_f32_e32 v24, v45, v46
	v_fma_f32 v0, -v39, v24, v0
	v_lshlrev_b32_e32 v39, 16, v50
	v_div_fmas_f32 v0, v0, v46, v24
	v_and_b32_e32 v45, 0xffff0000, v50
	v_mul_f32_e32 v24, 0xbfb8aa3b, v39
	v_exp_f32_e32 v46, v24
	v_mul_f32_e32 v24, 0xbfb8aa3b, v45
	v_exp_f32_e32 v47, v24
	v_div_fixup_f32 v24, v0, v44, v57
	v_pk_mul_f32 v[22:23], v[22:23], v[24:25]
	v_pk_add_f32 v[24:25], v[46:47], 1.0 op_sel_hi:[1,0]
	s_nop 0
	v_div_scale_f32 v0, s[52:53], v25, v25, v45
	v_rcp_f32_e32 v44, v0
	v_cvt_pk_bf16_f32 v21, v22, v23
	v_mov_b32_e32 v142, v20
	v_mov_b32_e32 v143, v21
	s_nop 1
	v_permlane32_swap_b32_e32 v140, v142
	v_permlane32_swap_b32_e32 v141, v143
	global_store_dwordx4 v[158:159], v[140:143], off offset:1024
	v_pk_mul_f32 v[20:21], v[26:27], v[38:39] op_sel_hi:[1,0]
	v_fma_f32 v22, -v0, v44, 1.0
	v_fmac_f32_e32 v44, v22, v44
	v_div_scale_f32 v22, vcc, v45, v25, v45
	v_mul_f32_e32 v23, v22, v44
	v_fma_f32 v26, -v0, v23, v22
	v_fmac_f32_e32 v23, v26, v44
	v_fma_f32 v0, -v0, v23, v22
	v_div_scale_f32 v22, s[52:53], v24, v24, v39
	v_rcp_f32_e32 v46, v22
	v_div_fmas_f32 v0, v0, v44, v23
	v_div_fixup_f32 v23, v0, v25, v45
	v_lshlrev_b32_e32 v44, 16, v51
	v_fma_f32 v0, -v22, v46, 1.0
	v_fmac_f32_e32 v46, v0, v46
	v_div_scale_f32 v0, vcc, v39, v24, v39
	v_mul_f32_e32 v25, v0, v46
	v_fma_f32 v26, -v22, v25, v0
	v_and_b32_e32 v45, 0xffff0000, v51
	v_fmac_f32_e32 v25, v26, v46
	v_mul_f32_e32 v26, 0xbfb8aa3b, v44
	v_mul_f32_e32 v27, 0xbfb8aa3b, v45
	v_exp_f32_e32 v26, v26
	v_exp_f32_e32 v27, v27
	v_fma_f32 v0, -v22, v25, v0
	v_div_fmas_f32 v0, v0, v46, v25
	v_div_fixup_f32 v22, v0, v24, v39
	v_pk_add_f32 v[26:27], v[26:27], 1.0 op_sel_hi:[1,0]
	v_pk_mul_f32 v[20:21], v[20:21], v[22:23]
	v_div_scale_f32 v25, s[52:53], v27, v27, v45
	v_rcp_f32_e32 v46, v25
	v_pk_mul_f32 v[22:23], v[28:29], v[38:39] op_sel_hi:[1,0]
	v_lshlrev_b32_e32 v39, 16, v52
	v_cvt_pk_bf16_f32 v20, v20, v21
	v_fma_f32 v0, -v25, v46, 1.0
	v_fmac_f32_e32 v46, v0, v46
	v_div_scale_f32 v0, vcc, v45, v27, v45
	v_mul_f32_e32 v24, v0, v46
	v_fma_f32 v28, -v25, v24, v0
	v_fmac_f32_e32 v24, v28, v46
	v_div_scale_f32 v28, s[52:53], v26, v26, v44
	v_rcp_f32_e32 v29, v28
	v_fma_f32 v0, -v25, v24, v0
	v_div_fmas_f32 v0, v0, v46, v24
	v_div_fixup_f32 v25, v0, v27, v45
	v_fma_f32 v0, -v28, v29, 1.0
	v_fmac_f32_e32 v29, v0, v29
	v_div_scale_f32 v0, vcc, v44, v26, v44
	v_mul_f32_e32 v24, v0, v29
	v_fma_f32 v27, -v28, v24, v0
	v_fmac_f32_e32 v24, v27, v29
	v_fma_f32 v0, -v28, v24, v0
	v_div_fmas_f32 v0, v0, v29, v24
	v_and_b32_e32 v27, 0xffff0000, v52
	v_mul_f32_e32 v24, 0xbfb8aa3b, v39
	v_exp_f32_e32 v28, v24
	v_mul_f32_e32 v24, 0xbfb8aa3b, v27
	v_exp_f32_e32 v29, v24
	v_div_fixup_f32 v24, v0, v26, v44
	v_pk_mul_f32 v[22:23], v[22:23], v[24:25]
	v_pk_mul_f32 v[2:3], v[2:3], v[38:39] op_sel_hi:[1,0]
	v_pk_add_f32 v[24:25], v[28:29], 1.0 op_sel_hi:[1,0]
	v_cvt_pk_bf16_f32 v21, v22, v23
	v_div_scale_f32 v0, s[52:53], v25, v25, v27
	v_rcp_f32_e32 v26, v0
	v_mov_b32_e32 v144, v20
	v_mov_b32_e32 v145, v21
	v_pk_mul_f32 v[20:21], v[30:31], v[38:39] op_sel_hi:[1,0]
	v_lshlrev_b32_e32 v30, 16, v53
	v_fma_f32 v22, -v0, v26, 1.0
	v_fmac_f32_e32 v26, v22, v26
	v_div_scale_f32 v22, vcc, v27, v25, v27
	v_mul_f32_e32 v23, v22, v26
	v_fma_f32 v28, -v0, v23, v22
	v_fmac_f32_e32 v23, v28, v26
	v_fma_f32 v0, -v0, v23, v22
	v_div_scale_f32 v22, s[52:53], v24, v24, v39
	v_rcp_f32_e32 v28, v22
	v_div_fmas_f32 v0, v0, v26, v23
	v_div_fixup_f32 v23, v0, v25, v27
	v_and_b32_e32 v29, 0xffff0000, v53
	v_fma_f32 v0, -v22, v28, 1.0
	v_fmac_f32_e32 v28, v0, v28
	v_div_scale_f32 v0, vcc, v39, v24, v39
	v_mul_f32_e32 v25, v0, v28
	v_fma_f32 v26, -v22, v25, v0
	v_fmac_f32_e32 v25, v26, v28
	v_mul_f32_e32 v26, 0xbfb8aa3b, v30
	v_mul_f32_e32 v27, 0xbfb8aa3b, v29
	v_exp_f32_e32 v26, v26
	v_exp_f32_e32 v27, v27
	v_fma_f32 v0, -v22, v25, v0
	v_div_fmas_f32 v0, v0, v28, v25
	v_div_fixup_f32 v22, v0, v24, v39
	v_pk_add_f32 v[26:27], v[26:27], 1.0 op_sel_hi:[1,0]
	v_pk_mul_f32 v[20:21], v[20:21], v[22:23]
	v_div_scale_f32 v25, s[52:53], v27, v27, v29
	v_rcp_f32_e32 v28, v25
	v_pk_mul_f32 v[22:23], v[32:33], v[38:39] op_sel_hi:[1,0]
	v_cvt_pk_bf16_f32 v20, v20, v21
	v_pk_mul_f32 v[4:5], v[4:5], v[38:39] op_sel_hi:[1,0]
	v_fma_f32 v0, -v25, v28, 1.0
	v_fmac_f32_e32 v28, v0, v28
	v_div_scale_f32 v0, vcc, v29, v27, v29
	v_mul_f32_e32 v24, v0, v28
	v_fma_f32 v31, -v25, v24, v0
	v_fmac_f32_e32 v24, v31, v28
	v_div_scale_f32 v31, s[52:53], v26, v26, v30
	v_rcp_f32_e32 v32, v31
	v_fma_f32 v0, -v25, v24, v0
	v_div_fmas_f32 v0, v0, v28, v24
	v_div_fixup_f32 v25, v0, v27, v29
	v_fma_f32 v0, -v31, v32, 1.0
	v_fmac_f32_e32 v32, v0, v32
	v_div_scale_f32 v0, vcc, v30, v26, v30
	v_mul_f32_e32 v24, v0, v32
	v_fma_f32 v27, -v31, v24, v0
	v_fmac_f32_e32 v24, v27, v32
	v_fma_f32 v0, -v31, v24, v0
	v_lshlrev_b32_e32 v27, 16, v34
	v_div_fmas_f32 v0, v0, v32, v24
	v_and_b32_e32 v31, 0xffff0000, v34
	v_mul_f32_e32 v24, 0xbfb8aa3b, v27
	v_exp_f32_e32 v28, v24
	v_mul_f32_e32 v24, 0xbfb8aa3b, v31
	v_exp_f32_e32 v29, v24
	v_div_fixup_f32 v24, v0, v26, v30
	v_pk_mul_f32 v[22:23], v[22:23], v[24:25]
	v_pk_add_f32 v[24:25], v[28:29], 1.0 op_sel_hi:[1,0]
	s_nop 0
	v_div_scale_f32 v0, s[52:53], v25, v25, v31
	v_rcp_f32_e32 v26, v0
	v_cvt_pk_bf16_f32 v21, v22, v23
	v_mov_b32_e32 v146, v20
	v_mov_b32_e32 v147, v21
	s_nop 1
	v_permlane32_swap_b32_e32 v144, v146
	v_permlane32_swap_b32_e32 v145, v147
	global_store_dwordx4 v[158:159], v[144:147], off offset:1056
	v_and_b32_e32 v29, 0xffff0000, v35
	v_fma_f32 v20, -v0, v26, 1.0
	v_fmac_f32_e32 v26, v20, v26
	v_div_scale_f32 v20, vcc, v31, v25, v31
	v_mul_f32_e32 v21, v20, v26
	v_fma_f32 v22, -v0, v21, v20
	v_fmac_f32_e32 v21, v22, v26
	v_fma_f32 v0, -v0, v21, v20
	v_div_scale_f32 v20, s[52:53], v24, v24, v27
	v_rcp_f32_e32 v28, v20
	v_div_fmas_f32 v0, v0, v26, v21
	v_div_fixup_f32 v21, v0, v25, v31
	v_lshlrev_b32_e32 v26, 16, v35
	v_fma_f32 v0, -v20, v28, 1.0
	v_fmac_f32_e32 v28, v0, v28
	v_div_scale_f32 v0, vcc, v27, v24, v27
	v_mul_f32_e32 v25, v0, v28
	v_fma_f32 v22, -v20, v25, v0
	v_fmac_f32_e32 v25, v22, v28
	v_mul_f32_e32 v22, 0xbfb8aa3b, v26
	v_mul_f32_e32 v23, 0xbfb8aa3b, v29
	v_exp_f32_e32 v22, v22
	v_exp_f32_e32 v23, v23
	v_fma_f32 v0, -v20, v25, v0
	v_div_fmas_f32 v0, v0, v28, v25
	v_div_fixup_f32 v20, v0, v24, v27
	v_pk_add_f32 v[22:23], v[22:23], 1.0 op_sel_hi:[1,0]
	v_pk_mul_f32 v[2:3], v[2:3], v[20:21]
	v_div_scale_f32 v25, s[52:53], v23, v23, v29
	v_rcp_f32_e32 v28, v25
	v_div_scale_f32 v24, s[52:53], v22, v22, v26
	v_and_b32_e32 v27, 0xffff0000, v36
	v_fma_f32 v0, -v25, v28, 1.0
	v_fmac_f32_e32 v28, v0, v28
	v_div_scale_f32 v0, vcc, v29, v23, v29
	v_mul_f32_e32 v20, v0, v28
	v_fma_f32 v21, -v25, v20, v0
	v_fmac_f32_e32 v20, v21, v28
	v_fma_f32 v0, -v25, v20, v0
	v_rcp_f32_e32 v25, v24
	v_div_fmas_f32 v0, v0, v28, v20
	v_div_fixup_f32 v21, v0, v23, v29
	v_cvt_pk_bf16_f32 v2, v2, v3
	v_fma_f32 v0, -v24, v25, 1.0
	v_fmac_f32_e32 v25, v0, v25
	v_div_scale_f32 v0, vcc, v26, v22, v26
	v_mul_f32_e32 v20, v0, v25
	v_fma_f32 v23, -v24, v20, v0
	v_fmac_f32_e32 v20, v23, v25
	v_fma_f32 v0, -v24, v20, v0
	v_lshlrev_b32_e32 v23, 16, v36
	v_div_fmas_f32 v0, v0, v25, v20
	v_mul_f32_e32 v20, 0xbfb8aa3b, v23
	v_exp_f32_e32 v24, v20
	v_mul_f32_e32 v20, 0xbfb8aa3b, v27
	v_exp_f32_e32 v25, v20
	v_div_fixup_f32 v20, v0, v22, v26
	v_pk_mul_f32 v[4:5], v[4:5], v[20:21]
	v_pk_add_f32 v[20:21], v[24:25], 1.0 op_sel_hi:[1,0]
	s_nop 0
	v_div_scale_f32 v0, s[52:53], v21, v21, v27
	v_rcp_f32_e32 v22, v0
	v_cvt_pk_bf16_f32 v3, v4, v5
	v_mov_b32_e32 v148, v2
	v_mov_b32_e32 v149, v3
	v_pk_mul_f32 v[2:3], v[6:7], v[38:39] op_sel_hi:[1,0]
	v_fma_f32 v4, -v0, v22, 1.0
	v_fmac_f32_e32 v22, v4, v22
	v_div_scale_f32 v4, vcc, v27, v21, v27
	v_mul_f32_e32 v5, v4, v22
	v_fma_f32 v6, -v0, v5, v4
	v_fmac_f32_e32 v5, v6, v22
	v_fma_f32 v0, -v0, v5, v4
	v_div_scale_f32 v4, s[52:53], v20, v20, v23
	v_rcp_f32_e32 v24, v4
	v_div_fmas_f32 v0, v0, v22, v5
	v_div_fixup_f32 v5, v0, v21, v27
	v_lshlrev_b32_e32 v22, 16, v37
	v_fma_f32 v0, -v4, v24, 1.0
	v_fmac_f32_e32 v24, v0, v24
	v_div_scale_f32 v0, vcc, v23, v20, v23
	v_mul_f32_e32 v21, v0, v24
	v_fma_f32 v6, -v4, v21, v0
	v_and_b32_e32 v25, 0xffff0000, v37
	v_fmac_f32_e32 v21, v6, v24
	v_mul_f32_e32 v6, 0xbfb8aa3b, v22
	v_mul_f32_e32 v7, 0xbfb8aa3b, v25
	v_exp_f32_e32 v6, v6
	v_exp_f32_e32 v7, v7
	v_fma_f32 v0, -v4, v21, v0
	v_div_fmas_f32 v0, v0, v24, v21
	v_div_fixup_f32 v4, v0, v20, v23
	v_pk_add_f32 v[6:7], v[6:7], 1.0 op_sel_hi:[1,0]
	v_pk_mul_f32 v[2:3], v[2:3], v[4:5]
	v_div_scale_f32 v21, s[52:53], v7, v7, v25
	v_rcp_f32_e32 v24, v21
	v_pk_mul_f32 v[4:5], v[8:9], v[38:39] op_sel_hi:[1,0]
	v_cvt_pk_bf16_f32 v2, v2, v3
	v_fma_f32 v0, -v21, v24, 1.0
	v_fmac_f32_e32 v24, v0, v24
	v_div_scale_f32 v0, vcc, v25, v7, v25
	v_mul_f32_e32 v8, v0, v24
	v_fma_f32 v9, -v21, v8, v0
	v_fmac_f32_e32 v8, v9, v24
	v_div_scale_f32 v9, s[52:53], v6, v6, v22
	v_rcp_f32_e32 v20, v9
	v_fma_f32 v0, -v21, v8, v0
	v_div_fmas_f32 v0, v0, v24, v8
	v_div_fixup_f32 v7, v0, v7, v25
	v_fma_f32 v0, -v9, v20, 1.0
	v_fmac_f32_e32 v20, v0, v20
	v_div_scale_f32 v0, vcc, v22, v6, v22
	v_mul_f32_e32 v8, v0, v20
	v_fma_f32 v21, -v9, v8, v0
	v_fmac_f32_e32 v8, v21, v20
	v_fma_f32 v0, -v9, v8, v0
	v_div_fmas_f32 v0, v0, v20, v8
	v_lshlrev_b32_e32 v20, 16, v40
	v_and_b32_e32 v21, 0xffff0000, v40
	v_mul_f32_e32 v8, 0xbfb8aa3b, v20
	v_mul_f32_e32 v9, 0xbfb8aa3b, v21
	v_exp_f32_e32 v8, v8
	v_exp_f32_e32 v9, v9
	v_div_fixup_f32 v6, v0, v6, v22
	v_pk_mul_f32 v[4:5], v[4:5], v[6:7]
	v_pk_add_f32 v[6:7], v[8:9], 1.0 op_sel_hi:[1,0]
	s_nop 0
	v_div_scale_f32 v0, s[52:53], v7, v7, v21
	v_rcp_f32_e32 v8, v0
	v_cvt_pk_bf16_f32 v3, v4, v5
	v_mov_b32_e32 v150, v2
	v_mov_b32_e32 v151, v3
	s_nop 1
	v_permlane32_swap_b32_e32 v148, v150
	v_permlane32_swap_b32_e32 v149, v151
	global_store_dwordx4 v[158:159], v[148:151], off offset:1088
	v_pk_mul_f32 v[2:3], v[10:11], v[38:39] op_sel_hi:[1,0]
	v_fma_f32 v4, -v0, v8, 1.0
	v_fmac_f32_e32 v8, v4, v8
	v_div_scale_f32 v4, vcc, v21, v7, v21
	v_mul_f32_e32 v5, v4, v8
	v_fma_f32 v9, -v0, v5, v4
	v_fmac_f32_e32 v5, v9, v8
	v_fma_f32 v0, -v0, v5, v4
	v_div_scale_f32 v4, s[52:53], v6, v6, v20
	v_rcp_f32_e32 v10, v4
	v_div_fmas_f32 v0, v0, v8, v5
	v_div_fixup_f32 v5, v0, v7, v21
	v_lshlrev_b32_e32 v21, 16, v41
	v_fma_f32 v0, -v4, v10, 1.0
	v_fmac_f32_e32 v10, v0, v10
	v_div_scale_f32 v0, vcc, v20, v6, v20
	v_mul_f32_e32 v7, v0, v10
	v_fma_f32 v8, -v4, v7, v0
	v_and_b32_e32 v11, 0xffff0000, v41
	v_fmac_f32_e32 v7, v8, v10
	v_mul_f32_e32 v8, 0xbfb8aa3b, v21
	v_mul_f32_e32 v9, 0xbfb8aa3b, v11
	v_exp_f32_e32 v8, v8
	v_exp_f32_e32 v9, v9
	v_fma_f32 v0, -v4, v7, v0
	v_div_fmas_f32 v0, v0, v10, v7
	v_div_fixup_f32 v4, v0, v6, v20
	v_pk_add_f32 v[8:9], v[8:9], 1.0 op_sel_hi:[1,0]
	v_pk_mul_f32 v[2:3], v[2:3], v[4:5]
	v_div_scale_f32 v7, s[52:53], v9, v9, v11
	v_rcp_f32_e32 v10, v7
	v_pk_mul_f32 v[4:5], v[12:13], v[38:39] op_sel_hi:[1,0]
	v_cvt_pk_bf16_f32 v2, v2, v3
	v_fma_f32 v0, -v7, v10, 1.0
	v_fmac_f32_e32 v10, v0, v10
	v_div_scale_f32 v0, vcc, v11, v9, v11
	v_mul_f32_e32 v6, v0, v10
	v_fma_f32 v12, -v7, v6, v0
	v_fmac_f32_e32 v6, v12, v10
	v_div_scale_f32 v12, s[52:53], v8, v8, v21
	v_rcp_f32_e32 v13, v12
	v_fma_f32 v0, -v7, v6, v0
	v_div_fmas_f32 v0, v0, v10, v6
	v_div_fixup_f32 v7, v0, v9, v11
	v_fma_f32 v0, -v12, v13, 1.0
	v_fmac_f32_e32 v13, v0, v13
	v_div_scale_f32 v0, vcc, v21, v8, v21
	v_mul_f32_e32 v6, v0, v13
	v_fma_f32 v9, -v12, v6, v0
	v_fmac_f32_e32 v6, v9, v13
	v_fma_f32 v0, -v12, v6, v0
	v_and_b32_e32 v9, 0xffff0000, v42
	v_div_fmas_f32 v0, v0, v13, v6
	v_lshlrev_b32_e32 v12, 16, v42
	v_mul_f32_e32 v6, 0xbfb8aa3b, v9
	v_exp_f32_e32 v11, v6
	v_mul_f32_e32 v6, 0xbfb8aa3b, v12
	v_exp_f32_e32 v10, v6
	v_div_fixup_f32 v6, v0, v8, v21
	v_pk_mul_f32 v[4:5], v[4:5], v[6:7]
	v_and_b32_e32 v13, 0xffff0000, v43
	v_pk_add_f32 v[6:7], v[10:11], 1.0 op_sel_hi:[1,0]
	v_cvt_pk_bf16_f32 v3, v4, v5
	v_div_scale_f32 v0, s[52:53], v7, v7, v9
	v_rcp_f32_e32 v8, v0
	v_lshlrev_b32_e32 v11, 16, v43
	v_mov_b32_e32 v152, v2
	v_mov_b32_e32 v153, v3
	v_pk_mul_f32 v[2:3], v[14:15], v[38:39] op_sel_hi:[1,0]
	v_fma_f32 v4, -v0, v8, 1.0
	v_fmac_f32_e32 v8, v4, v8
	v_div_scale_f32 v4, vcc, v9, v7, v9
	v_mul_f32_e32 v5, v4, v8
	v_fma_f32 v10, -v0, v5, v4
	v_fmac_f32_e32 v5, v10, v8
	v_fma_f32 v0, -v0, v5, v4
	v_div_scale_f32 v4, s[52:53], v6, v6, v12
	v_rcp_f32_e32 v10, v4
	v_div_fmas_f32 v0, v0, v8, v5
	v_div_fixup_f32 v5, v0, v7, v9
	v_mul_f32_e32 v9, 0xbfb8aa3b, v13
	v_fma_f32 v0, -v4, v10, 1.0
	v_fmac_f32_e32 v10, v0, v10
	v_div_scale_f32 v0, vcc, v12, v6, v12
	v_mul_f32_e32 v7, v0, v10
	v_fma_f32 v8, -v4, v7, v0
	v_fmac_f32_e32 v7, v8, v10
	v_mul_f32_e32 v8, 0xbfb8aa3b, v11
	v_exp_f32_e32 v8, v8
	v_exp_f32_e32 v9, v9
	v_fma_f32 v0, -v4, v7, v0
	v_div_fmas_f32 v0, v0, v10, v7
	v_div_fixup_f32 v4, v0, v6, v12
	v_pk_add_f32 v[8:9], v[8:9], 1.0 op_sel_hi:[1,0]
	v_pk_mul_f32 v[2:3], v[2:3], v[4:5]
	v_div_scale_f32 v7, s[52:53], v9, v9, v13
	v_rcp_f32_e32 v10, v7
	v_pk_mul_f32 v[4:5], v[16:17], v[38:39] op_sel_hi:[1,0]
	v_cvt_pk_bf16_f32 v2, v2, v3
	v_fma_f32 v0, -v7, v10, 1.0
	v_fmac_f32_e32 v10, v0, v10
	v_div_scale_f32 v0, vcc, v13, v9, v13
	v_mul_f32_e32 v6, v0, v10
	v_fma_f32 v12, -v7, v6, v0
	v_fmac_f32_e32 v6, v12, v10
	v_div_scale_f32 v12, s[52:53], v8, v8, v11
	v_rcp_f32_e32 v14, v12
	v_fma_f32 v0, -v7, v6, v0
	v_div_fmas_f32 v0, v0, v10, v6
	v_div_fixup_f32 v7, v0, v9, v13
	v_fma_f32 v0, -v12, v14, 1.0
	v_fmac_f32_e32 v14, v0, v14
	v_div_scale_f32 v0, vcc, v11, v8, v11
	v_mul_f32_e32 v6, v0, v14
	v_fma_f32 v9, -v12, v6, v0
	v_fmac_f32_e32 v6, v9, v14
	v_fma_f32 v0, -v12, v6, v0
	v_div_fmas_f32 v0, v0, v14, v6
	v_div_fixup_f32 v6, v0, v8, v11
	v_pk_mul_f32 v[4:5], v[4:5], v[6:7]
	s_nop 0
	v_cvt_pk_bf16_f32 v3, v4, v5
	v_mov_b32_e32 v154, v2
	v_mov_b32_e32 v155, v3
	s_nop 1
	v_permlane32_swap_b32_e32 v152, v154
	v_permlane32_swap_b32_e32 v153, v155
	global_store_dwordx4 v[158:159], v[152:155], off offset:1120
	s_and_saveexec_b64 s[52:53], s[0:1]
	s_cbranch_execz .LBB0_422
